# baseline (speedup 1.0000x reference)
; DI void convT_all(KP pp, char* ws, float* lds, int tid) {
;     ...
;     __syncthreads();
;     {
;       float4 v[16];
;       const float* sp = src + (size_t)(k0 + kr) * Nsrc + sn;
; #pragma unroll
;       for (int ps = 0; ps < 16; ps++) v[ps] = zero ? make_float4(0.f, 0.f, 0.f, 0.f) : *(const float4*)(sp + (size_t)ps * 8 * Nsrc);
; #pragma unroll
;       for (int ps = 0; ps < 16; ps++) {
;         const float g = gain ? gain[k0 + kr + ps * 8] : 1.f;
;         float* lp = lds + (kr + ps * 8) * 129 + n4 * 4;
;         lp[0] = v[ps].x * g; lp[1] = v[ps].y * g; lp[2] = v[ps].z * g; lp[3] = v[ps].w * g;
;       }
;     }
;     __syncthreads();
;     u16* dp = dst + (size_t)(nt * 128 + on) * K + k0 + okh * 64;
; #pragma unroll
;     for (int j8 = 0; j8 < 8; j8++) {
;       const float* lp = lds + (okh * 64 + j8 * 8) * 129 + on;
;       *(uint4*)(dp + j8 * 8) = make_uint4(pack2(lp[0], lp[129]), pack2(lp[2 * 129], lp[3 * 129]), pack2(lp[4 * 129], lp[5 * 129]), pack2(lp[6 * 129], lp[7 * 129]));
;     }
.LBB0_580:
	v_add_u32_e32 v0, 0xe1c0, v77
	ds_write2_b32 v0, v6, v7 offset1:1
	v_add_u32_e32 v0, 0xe1c8, v77
	ds_write2_b32 v0, v4, v5 offset1:1
	s_waitcnt vmcnt(0)
	v_pk_mul_f32 v[0:1], v[16:17], v[20:21] op_sel_hi:[1,0]
	v_add_u32_e32 v2, 0xf1e0, v77
	ds_write2_b32 v2, v0, v1 offset1:1
	v_pk_mul_f32 v[0:1], v[18:19], v[20:21] op_sel_hi:[1,0]
	v_add_u32_e32 v2, 0xf1e8, v77
	v_add_u32_e32 v4, 0x800, v76
	ds_write2_b32 v2, v0, v1 offset1:1
	s_waitcnt lgkmcnt(0)
	s_barrier
	v_and_b32_e32 v80, 7, v152
	v_bfe_u32 v81, v152, 3, 3
	v_bfe_u32 v82, v152, 6, 1
	v_lshrrev_b32_e32 v83, 7, v152
	v_lshl_add_u32 v84, v83, 3, v80
	v_lshlrev_b32_e32 v85, 6, v82
	v_lshl_add_u32 v85, v81, 3, v85
	v_mul_u32_u24_e32 v86, 0x81, v85
	v_add_u32_e32 v86, v86, v84
	v_lshlrev_b32_e32 v86, 2, v86
	v_add_u32_e32 v87, s11, v84
	v_mul_lo_u32 v88, v87, s24
	v_add3_u32 v88, v88, v85, s10
	v_ashrrev_i32_e32 v89, 31, v88
	v_lshl_add_u64 v[98:99], v[88:89], 1, s[8:9]
	v_mov_b32_e32 v100, s24
	v_lshlrev_b32_e32 v100, 5, v100
	v_mov_b32_e32 v101, 0
	s_ashr_i32 s11, s10, 31
	ds_read_b32 v102, v86 offset:0
	ds_read_b32 v103, v86 offset:516
	ds_read_b32 v104, v86 offset:1032
	ds_read_b32 v105, v86 offset:1548
	ds_read_b32 v106, v86 offset:2064
	ds_read_b32 v107, v86 offset:2580
	ds_read_b32 v108, v86 offset:3096
	ds_read_b32 v109, v86 offset:3612
	s_waitcnt lgkmcnt(0)
	v_cvt_pk_bf16_f32 v110, v102, v103
	v_cvt_pk_bf16_f32 v111, v104, v105
	v_cvt_pk_bf16_f32 v112, v106, v107
	v_cvt_pk_bf16_f32 v113, v108, v109
	global_store_dwordx4 v[98:99], v[110:113], off
	v_lshl_add_u64 v[98:99], v[98:99], 0, v[100:101]
	ds_read_b32 v102, v86 offset:64
	ds_read_b32 v103, v86 offset:580
	ds_read_b32 v104, v86 offset:1096
	ds_read_b32 v105, v86 offset:1612
	ds_read_b32 v106, v86 offset:2128
	ds_read_b32 v107, v86 offset:2644
	ds_read_b32 v108, v86 offset:3160
	ds_read_b32 v109, v86 offset:3676
	s_waitcnt lgkmcnt(0)
	v_cvt_pk_bf16_f32 v110, v102, v103
	v_cvt_pk_bf16_f32 v111, v104, v105
	v_cvt_pk_bf16_f32 v112, v106, v107
	v_cvt_pk_bf16_f32 v113, v108, v109
	global_store_dwordx4 v[98:99], v[110:113], off
	v_lshl_add_u64 v[98:99], v[98:99], 0, v[100:101]
	ds_read_b32 v102, v86 offset:128
	ds_read_b32 v103, v86 offset:644
	ds_read_b32 v104, v86 offset:1160
	ds_read_b32 v105, v86 offset:1676
	ds_read_b32 v106, v86 offset:2192
	ds_read_b32 v107, v86 offset:2708
	ds_read_b32 v108, v86 offset:3224
	ds_read_b32 v109, v86 offset:3740
	s_waitcnt lgkmcnt(0)
	v_cvt_pk_bf16_f32 v110, v102, v103
	v_cvt_pk_bf16_f32 v111, v104, v105
	v_cvt_pk_bf16_f32 v112, v106, v107
	v_cvt_pk_bf16_f32 v113, v108, v109
	global_store_dwordx4 v[98:99], v[110:113], off
	v_lshl_add_u64 v[98:99], v[98:99], 0, v[100:101]
	ds_read_b32 v102, v86 offset:192
	ds_read_b32 v103, v86 offset:708
	ds_read_b32 v104, v86 offset:1224
	ds_read_b32 v105, v86 offset:1740
	ds_read_b32 v106, v86 offset:2256
	ds_read_b32 v107, v86 offset:2772
	ds_read_b32 v108, v86 offset:3288
	ds_read_b32 v109, v86 offset:3804
	s_waitcnt lgkmcnt(0)
	v_cvt_pk_bf16_f32 v110, v102, v103
	v_cvt_pk_bf16_f32 v111, v104, v105
	v_cvt_pk_bf16_f32 v112, v106, v107
	v_cvt_pk_bf16_f32 v113, v108, v109
	global_store_dwordx4 v[98:99], v[110:113], off
	v_lshl_add_u64 v[98:99], v[98:99], 0, v[100:101]
	ds_read_b32 v102, v86 offset:256
	ds_read_b32 v103, v86 offset:772
	ds_read_b32 v104, v86 offset:1288
	ds_read_b32 v105, v86 offset:1804
	ds_read_b32 v106, v86 offset:2320
	ds_read_b32 v107, v86 offset:2836
	ds_read_b32 v108, v86 offset:3352
	ds_read_b32 v109, v86 offset:3868
	s_waitcnt lgkmcnt(0)
	v_cvt_pk_bf16_f32 v110, v102, v103
	v_cvt_pk_bf16_f32 v111, v104, v105
	v_cvt_pk_bf16_f32 v112, v106, v107
	v_cvt_pk_bf16_f32 v113, v108, v109
	global_store_dwordx4 v[98:99], v[110:113], off
	v_lshl_add_u64 v[98:99], v[98:99], 0, v[100:101]
	ds_read_b32 v102, v86 offset:320
	ds_read_b32 v103, v86 offset:836
	ds_read_b32 v104, v86 offset:1352
	ds_read_b32 v105, v86 offset:1868
	ds_read_b32 v106, v86 offset:2384
	ds_read_b32 v107, v86 offset:2900
	ds_read_b32 v108, v86 offset:3416
	ds_read_b32 v109, v86 offset:3932
	s_waitcnt lgkmcnt(0)
	v_cvt_pk_bf16_f32 v110, v102, v103
	v_cvt_pk_bf16_f32 v111, v104, v105
	v_cvt_pk_bf16_f32 v112, v106, v107
	v_cvt_pk_bf16_f32 v113, v108, v109
	global_store_dwordx4 v[98:99], v[110:113], off
	v_lshl_add_u64 v[98:99], v[98:99], 0, v[100:101]
	ds_read_b32 v102, v86 offset:384
	ds_read_b32 v103, v86 offset:900
	ds_read_b32 v104, v86 offset:1416
	ds_read_b32 v105, v86 offset:1932
	ds_read_b32 v106, v86 offset:2448
	ds_read_b32 v107, v86 offset:2964
	ds_read_b32 v108, v86 offset:3480
	ds_read_b32 v109, v86 offset:3996
	s_waitcnt lgkmcnt(0)
	v_cvt_pk_bf16_f32 v110, v102, v103
	v_cvt_pk_bf16_f32 v111, v104, v105
	v_cvt_pk_bf16_f32 v112, v106, v107
	v_cvt_pk_bf16_f32 v113, v108, v109
	global_store_dwordx4 v[98:99], v[110:113], off
	v_lshl_add_u64 v[98:99], v[98:99], 0, v[100:101]
	ds_read_b32 v102, v86 offset:448
	ds_read_b32 v103, v86 offset:964
	ds_read_b32 v104, v86 offset:1480
	ds_read_b32 v105, v86 offset:1996
	ds_read_b32 v106, v86 offset:2512
	ds_read_b32 v107, v86 offset:3028
	ds_read_b32 v108, v86 offset:3544
	ds_read_b32 v109, v86 offset:4060
	s_waitcnt lgkmcnt(0)
	v_cvt_pk_bf16_f32 v110, v102, v103
	v_cvt_pk_bf16_f32 v111, v104, v105
	v_cvt_pk_bf16_f32 v112, v106, v107
	v_cvt_pk_bf16_f32 v113, v108, v109
	global_store_dwordx4 v[98:99], v[110:113], off
	s_add_i32 s1, s1, s40
	s_cmpk_lt_i32 s1, 0x1098
	s_cbranch_scc0 .LBB0_658
